# MLA fast loop: next iteration LDS addresses and V prefetch issued before the end barrier, K LDS writes behind the sixth QK MFMA, pointer bases folded once per item
# speedup vs baseline: 1.0078x; 1.0078x over previous
.Lmf_entry:
	v_mov_b32_e32 v239, 0
	v_lshl_add_u64 v[174:175], s[98:99], 0, v[174:175]
	v_lshl_add_u64 v[176:177], s[98:99], 0, v[176:177]
	v_lshl_add_u64 v[178:179], s[78:79], 0, v[178:179]
	v_lshl_add_u64 v[180:181], s[78:79], 0, v[180:181]
	v_lshl_add_u64 v[182:183], s[78:79], 0, v[182:183]
	s_mov_b32 s12, 0
	s_mov_b32 s0, 0xaa00
	v_add3_u32 v131, s12, v132, v204
	v_add3_u32 v173, s12, v189, v205
	v_add3_u32 v236, s0, v191, v192
	v_add3_u32 v237, s0, v194, v195
	v_add3_u32 v238, s0, v197, v198
	v_add_u32_e32 v155, 0x8800, v173
	v_add_u32_e32 v173, 0x6800, v173
	global_load_dwordx4 v[240:243], v[174:175], off offset:256
	global_load_dwordx4 v[244:247], v[176:177], off offset:256
.Lmf_loop:
	s_setprio 0
	ds_read_b128 v[122:125], v131
	ds_read_b128 v[126:129], v131 offset:6656
	ds_read_b128 v[184:187], v131 offset:13312
	ds_read_b128 v[208:211], v131 offset:19968
	ds_read_b128 v[212:215], v131 offset:32
	ds_read_b128 v[216:219], v131 offset:6688
	s_waitcnt lgkmcnt(5)
	v_mfma_f32_32x32x16_bf16 v[82:97], v[122:125], v[102:105], 0
	ds_read_b128 v[122:125], v131 offset:13344
	s_waitcnt lgkmcnt(5)
	v_mfma_f32_32x32x16_bf16 v[66:81], v[126:129], v[102:105], 0
	ds_read_b128 v[126:129], v131 offset:20000
	s_waitcnt lgkmcnt(5)
	v_mfma_f32_32x32x16_bf16 v[50:65], v[184:187], v[102:105], 0
	ds_read_b128 v[184:187], v131 offset:64
	s_waitcnt lgkmcnt(5)
	v_mfma_f32_32x32x16_bf16 v[34:49], v[208:211], v[102:105], 0
	ds_read_b128 v[208:211], v131 offset:6720
	s_waitcnt lgkmcnt(5)
	v_mfma_f32_32x32x16_bf16 v[82:97], v[212:215], v[110:113], v[82:97]
	ds_read_b128 v[212:215], v131 offset:13376
	s_waitcnt lgkmcnt(5)
	v_mfma_f32_32x32x16_bf16 v[66:81], v[216:219], v[110:113], v[66:81]
	s_waitcnt vmcnt(2)
	ds_write_b128 v236, v[224:227]
	ds_write_b128 v237, v[228:231]
	ds_write_b128 v238, v[232:235]
	ds_read_b128 v[216:219], v131 offset:20032
	s_waitcnt lgkmcnt(5)
	v_mfma_f32_32x32x16_bf16 v[50:65], v[122:125], v[110:113], v[50:65]
	ds_read_b128 v[122:125], v131 offset:96
	s_waitcnt lgkmcnt(5)
	v_mfma_f32_32x32x16_bf16 v[34:49], v[126:129], v[110:113], v[34:49]
	ds_read_b128 v[126:129], v131 offset:6752
	s_waitcnt lgkmcnt(5)
	v_mfma_f32_32x32x16_bf16 v[82:97], v[184:187], v[98:101], v[82:97]
	ds_read_b128 v[184:187], v131 offset:13408
	s_waitcnt lgkmcnt(5)
	v_mfma_f32_32x32x16_bf16 v[66:81], v[208:211], v[98:101], v[66:81]
	ds_read_b128 v[208:211], v131 offset:20064
	s_waitcnt lgkmcnt(5)
	v_mfma_f32_32x32x16_bf16 v[50:65], v[212:215], v[98:101], v[50:65]
	ds_read_b128 v[212:215], v131 offset:128
	s_waitcnt lgkmcnt(5)
	v_mfma_f32_32x32x16_bf16 v[34:49], v[216:219], v[98:101], v[34:49]
	ds_read_b128 v[216:219], v131 offset:6784
	s_waitcnt lgkmcnt(5)
	v_mfma_f32_32x32x16_bf16 v[82:97], v[122:125], v[106:109], v[82:97]
	ds_read_b128 v[122:125], v131 offset:13440
	s_waitcnt lgkmcnt(5)
	v_mfma_f32_32x32x16_bf16 v[66:81], v[126:129], v[106:109], v[66:81]
	ds_read_b128 v[126:129], v131 offset:20096
	s_waitcnt lgkmcnt(5)
	v_mfma_f32_32x32x16_bf16 v[50:65], v[184:187], v[106:109], v[50:65]
	ds_read_b128 v[184:187], v131 offset:160
	s_waitcnt lgkmcnt(5)
	v_mfma_f32_32x32x16_bf16 v[34:49], v[208:211], v[106:109], v[34:49]
	ds_read_b128 v[208:211], v131 offset:6816
	s_waitcnt lgkmcnt(5)
	v_mfma_f32_32x32x16_bf16 v[82:97], v[212:215], v[118:121], v[82:97]
	ds_read_b128 v[212:215], v131 offset:13472
	s_waitcnt lgkmcnt(5)
	v_mfma_f32_32x32x16_bf16 v[66:81], v[216:219], v[118:121], v[66:81]
	ds_read_b128 v[216:219], v131 offset:20128
	s_waitcnt lgkmcnt(5)
	v_mfma_f32_32x32x16_bf16 v[50:65], v[122:125], v[118:121], v[50:65]
	s_waitcnt lgkmcnt(4)
	v_mfma_f32_32x32x16_bf16 v[34:49], v[126:129], v[118:121], v[34:49]
	s_waitcnt lgkmcnt(3)
	v_mfma_f32_32x32x16_bf16 v[82:97], v[184:187], v[114:117], v[82:97]
	s_waitcnt lgkmcnt(2)
	v_mfma_f32_32x32x16_bf16 v[66:81], v[208:211], v[114:117], v[66:81]
	s_waitcnt lgkmcnt(1)
	v_mfma_f32_32x32x16_bf16 v[50:65], v[212:215], v[114:117], v[50:65]
	s_waitcnt lgkmcnt(0)
	v_mfma_f32_32x32x16_bf16 v[34:49], v[216:219], v[114:117], v[34:49]
	s_barrier
	s_setprio 1
	ds_read2_b64 v[122:125], v173 offset1:2
	ds_read2_b64 v[126:129], v155 offset0:32 offset1:34
	ds_read2_b64 v[184:187], v173 offset0:4 offset1:6
	ds_read2_b64 v[208:211], v155 offset0:36 offset1:38
	ds_read2_b64 v[212:215], v173 offset0:8 offset1:10
	ds_read2_b64 v[216:219], v155 offset0:40 offset1:42
	v_exp_f32_e32 v82, v82
	v_exp_f32_e32 v83, v83
	v_exp_f32_e32 v84, v84
	v_exp_f32_e32 v85, v85
	v_exp_f32_e32 v86, v86
	v_exp_f32_e32 v87, v87
	v_exp_f32_e32 v88, v88
	v_exp_f32_e32 v89, v89
	v_add_f32_e32 v1, v82, v1
	v_add_f32_e32 v239, v83, v239
	v_add_f32_e32 v1, v84, v1
	v_add_f32_e32 v239, v85, v239
	v_add_f32_e32 v1, v86, v1
	v_add_f32_e32 v239, v87, v239
	v_add_f32_e32 v1, v88, v1
	v_add_f32_e32 v239, v89, v239
	v_cvt_pk_bf16_f32 v82, v82, v83
	v_cvt_pk_bf16_f32 v83, v84, v85
	v_cvt_pk_bf16_f32 v84, v86, v87
	v_cvt_pk_bf16_f32 v85, v88, v89
	s_waitcnt lgkmcnt(4)
	v_exp_f32_e32 v90, v90
	v_exp_f32_e32 v91, v91
	v_exp_f32_e32 v92, v92
	v_exp_f32_e32 v93, v93
	v_mfma_f32_32x32x16_bf16 v[18:33], v[122:125], v[82:85], v[18:33]
	v_exp_f32_e32 v94, v94
	v_exp_f32_e32 v95, v95
	v_exp_f32_e32 v96, v96
	v_exp_f32_e32 v97, v97
	v_mfma_f32_32x32x16_bf16 v[2:17], v[126:129], v[82:85], v[2:17]
	ds_read2_b64 v[122:125], v173 offset0:12 offset1:14
	ds_read2_b64 v[126:129], v155 offset0:44 offset1:46
	v_add_f32_e32 v1, v90, v1
	v_add_f32_e32 v239, v91, v239
	v_add_f32_e32 v1, v92, v1
	v_add_f32_e32 v239, v93, v239
	v_add_f32_e32 v1, v94, v1
	v_add_f32_e32 v239, v95, v239
	v_add_f32_e32 v1, v96, v1
	v_add_f32_e32 v239, v97, v239
	v_cvt_pk_bf16_f32 v90, v90, v91
	v_cvt_pk_bf16_f32 v91, v92, v93
	v_cvt_pk_bf16_f32 v92, v94, v95
	v_cvt_pk_bf16_f32 v93, v96, v97
	s_waitcnt lgkmcnt(4)
	v_exp_f32_e32 v66, v66
	v_exp_f32_e32 v67, v67
	v_exp_f32_e32 v68, v68
	v_exp_f32_e32 v69, v69
	v_mfma_f32_32x32x16_bf16 v[18:33], v[184:187], v[90:93], v[18:33]
	v_exp_f32_e32 v70, v70
	v_exp_f32_e32 v71, v71
	v_exp_f32_e32 v72, v72
	v_exp_f32_e32 v73, v73
	v_mfma_f32_32x32x16_bf16 v[2:17], v[208:211], v[90:93], v[2:17]
	ds_read2_b64 v[184:187], v173 offset0:16 offset1:18
	ds_read2_b64 v[208:211], v155 offset0:48 offset1:50
	v_add_f32_e32 v1, v66, v1
	v_add_f32_e32 v239, v67, v239
	v_add_f32_e32 v1, v68, v1
	v_add_f32_e32 v239, v69, v239
	v_add_f32_e32 v1, v70, v1
	v_add_f32_e32 v239, v71, v239
	v_add_f32_e32 v1, v72, v1
	v_add_f32_e32 v239, v73, v239
	v_cvt_pk_bf16_f32 v66, v66, v67
	v_cvt_pk_bf16_f32 v67, v68, v69
	v_cvt_pk_bf16_f32 v68, v70, v71
	v_cvt_pk_bf16_f32 v69, v72, v73
	s_waitcnt lgkmcnt(4)
	v_exp_f32_e32 v74, v74
	v_exp_f32_e32 v75, v75
	v_exp_f32_e32 v76, v76
	v_exp_f32_e32 v77, v77
	v_mfma_f32_32x32x16_bf16 v[18:33], v[212:215], v[66:69], v[18:33]
	v_exp_f32_e32 v78, v78
	v_exp_f32_e32 v79, v79
	v_exp_f32_e32 v80, v80
	v_exp_f32_e32 v81, v81
	v_mfma_f32_32x32x16_bf16 v[2:17], v[216:219], v[66:69], v[2:17]
	ds_read2_b64 v[212:215], v173 offset0:20 offset1:22
	ds_read2_b64 v[216:219], v155 offset0:52 offset1:54
	v_add_f32_e32 v1, v74, v1
	v_add_f32_e32 v239, v75, v239
	v_add_f32_e32 v1, v76, v1
	v_add_f32_e32 v239, v77, v239
	v_add_f32_e32 v1, v78, v1
	v_add_f32_e32 v239, v79, v239
	v_add_f32_e32 v1, v80, v1
	v_add_f32_e32 v239, v81, v239
	v_cvt_pk_bf16_f32 v74, v74, v75
	v_cvt_pk_bf16_f32 v75, v76, v77
	v_cvt_pk_bf16_f32 v76, v78, v79
	v_cvt_pk_bf16_f32 v77, v80, v81
	s_waitcnt lgkmcnt(4)
	v_exp_f32_e32 v50, v50
	v_exp_f32_e32 v51, v51
	v_exp_f32_e32 v52, v52
	v_exp_f32_e32 v53, v53
	v_mfma_f32_32x32x16_bf16 v[18:33], v[122:125], v[74:77], v[18:33]
	v_exp_f32_e32 v54, v54
	v_exp_f32_e32 v55, v55
	v_exp_f32_e32 v56, v56
	v_exp_f32_e32 v57, v57
	v_mfma_f32_32x32x16_bf16 v[2:17], v[126:129], v[74:77], v[2:17]
	ds_read2_b64 v[122:125], v173 offset0:24 offset1:26
	ds_read2_b64 v[126:129], v155 offset0:56 offset1:58
	global_load_dwordx4 v[224:227], v[182:183], off
	global_load_dwordx4 v[228:231], v[180:181], off
	global_load_dwordx4 v[232:235], v[178:179], off
	v_add_f32_e32 v1, v50, v1
	v_add_f32_e32 v239, v51, v239
	v_add_f32_e32 v1, v52, v1
	v_add_f32_e32 v239, v53, v239
	v_add_f32_e32 v1, v54, v1
	v_add_f32_e32 v239, v55, v239
	v_add_f32_e32 v1, v56, v1
	v_add_f32_e32 v239, v57, v239
	v_cvt_pk_bf16_f32 v50, v50, v51
	v_cvt_pk_bf16_f32 v51, v52, v53
	v_cvt_pk_bf16_f32 v52, v54, v55
	v_cvt_pk_bf16_f32 v53, v56, v57
	s_waitcnt lgkmcnt(4)
	v_exp_f32_e32 v58, v58
	v_exp_f32_e32 v59, v59
	v_exp_f32_e32 v60, v60
	v_exp_f32_e32 v61, v61
	v_mfma_f32_32x32x16_bf16 v[18:33], v[184:187], v[50:53], v[18:33]
	v_exp_f32_e32 v62, v62
	v_exp_f32_e32 v63, v63
	v_exp_f32_e32 v64, v64
	v_exp_f32_e32 v65, v65
	v_mfma_f32_32x32x16_bf16 v[2:17], v[208:211], v[50:53], v[2:17]
	ds_read2_b64 v[184:187], v173 offset0:28 offset1:30
	ds_read2_b64 v[208:211], v155 offset0:60 offset1:62
	v_add_f32_e32 v1, v58, v1
	v_add_f32_e32 v239, v59, v239
	v_add_f32_e32 v1, v60, v1
	v_add_f32_e32 v239, v61, v239
	v_add_f32_e32 v1, v62, v1
	v_add_f32_e32 v239, v63, v239
	v_add_f32_e32 v1, v64, v1
	v_add_f32_e32 v239, v65, v239
	v_cvt_pk_bf16_f32 v58, v58, v59
	v_cvt_pk_bf16_f32 v59, v60, v61
	v_cvt_pk_bf16_f32 v60, v62, v63
	v_cvt_pk_bf16_f32 v61, v64, v65
	s_waitcnt lgkmcnt(4)
	v_exp_f32_e32 v34, v34
	v_exp_f32_e32 v35, v35
	v_exp_f32_e32 v36, v36
	v_exp_f32_e32 v37, v37
	v_mfma_f32_32x32x16_bf16 v[18:33], v[212:215], v[58:61], v[18:33]
	v_exp_f32_e32 v38, v38
	v_exp_f32_e32 v39, v39
	v_exp_f32_e32 v40, v40
	v_exp_f32_e32 v41, v41
	v_mfma_f32_32x32x16_bf16 v[2:17], v[216:219], v[58:61], v[2:17]
	v_lshl_add_u64 v[174:175], v[174:175], 0, s[6:7]
	v_lshl_add_u64 v[176:177], v[176:177], 0, s[6:7]
	v_lshl_add_u64 v[178:179], v[178:179], 0, s[8:9]
	v_lshl_add_u64 v[180:181], v[180:181], 0, s[8:9]
	v_lshl_add_u64 v[182:183], v[182:183], 0, s[8:9]
	v_add_f32_e32 v1, v34, v1
	v_add_f32_e32 v239, v35, v239
	v_add_f32_e32 v1, v36, v1
	v_add_f32_e32 v239, v37, v239
	v_add_f32_e32 v1, v38, v1
	v_add_f32_e32 v239, v39, v239
	v_add_f32_e32 v1, v40, v1
	v_add_f32_e32 v239, v41, v239
	v_cvt_pk_bf16_f32 v34, v34, v35
	v_cvt_pk_bf16_f32 v35, v36, v37
	v_cvt_pk_bf16_f32 v36, v38, v39
	v_cvt_pk_bf16_f32 v37, v40, v41
	s_waitcnt lgkmcnt(2)
	v_exp_f32_e32 v42, v42
	v_exp_f32_e32 v43, v43
	v_exp_f32_e32 v44, v44
	v_exp_f32_e32 v45, v45
	v_mfma_f32_32x32x16_bf16 v[18:33], v[122:125], v[34:37], v[18:33]
	v_exp_f32_e32 v46, v46
	v_exp_f32_e32 v47, v47
	v_exp_f32_e32 v48, v48
	v_exp_f32_e32 v49, v49
	v_mfma_f32_32x32x16_bf16 v[2:17], v[126:129], v[34:37], v[2:17]
	v_add_f32_e32 v1, v42, v1
	v_add_f32_e32 v239, v43, v239
	v_add_f32_e32 v1, v44, v1
	v_add_f32_e32 v239, v45, v239
	v_add_f32_e32 v1, v46, v1
	v_add_f32_e32 v239, v47, v239
	v_add_f32_e32 v1, v48, v1
	v_add_f32_e32 v239, v49, v239
	v_cvt_pk_bf16_f32 v42, v42, v43
	v_cvt_pk_bf16_f32 v43, v44, v45
	v_cvt_pk_bf16_f32 v44, v46, v47
	v_cvt_pk_bf16_f32 v45, v48, v49
	s_waitcnt lgkmcnt(0)
	s_nop 0
	v_mfma_f32_32x32x16_bf16 v[18:33], v[184:187], v[42:45], v[18:33]
	v_mfma_f32_32x32x16_bf16 v[2:17], v[208:211], v[42:45], v[2:17]
	s_add_i32 s13, s13, 1
	v_add_u32_e32 v220, s0, v200
	v_add3_u32 v221, v220, v202, s44
	v_add3_u32 v220, v220, v203, s44
	s_waitcnt vmcnt(3)
	ds_write2_b64 v221, v[240:241], v[242:243] offset1:1
	ds_write2_b64 v220, v[244:245], v[246:247] offset1:1
	v_add3_u32 v131, s0, v132, v204
	v_add3_u32 v173, s0, v189, v205
	v_add3_u32 v236, s12, v191, v192
	v_add3_u32 v237, s12, v194, v195
	v_add3_u32 v238, s12, v197, v198
	v_add_u32_e32 v155, 0x8800, v173
	v_add_u32_e32 v173, 0x6800, v173
	s_cmp_eq_u32 s34, s13
	s_waitcnt lgkmcnt(0)
	global_load_dwordx4 v[240:243], v[174:175], off offset:256
	global_load_dwordx4 v[244:247], v[176:177], off offset:256
	s_barrier
	s_cbranch_scc1 .Lmf_final
	s_xor_b32 s0, s0, 0xaa00
	s_xor_b32 s12, s12, 0xaa00
	s_branch .Lmf_loop
